# attention K/V tiles staged by LDS-DMA (global_load_lds_dwordx4) into an unpadded lane-linear LDS image with a source-side XOR chunk swizzle mirrored on the fragment reads; no staging VGPRs or ds_write
# speedup vs baseline: 1.0258x; 1.0090x over previous
.LBB0_747:
	s_and_b64 vcc, exec, s[10:11]
	s_cbranch_vccz .LBB0_751
	v_mov_b32_e32 v10, v232
	v_and_b32_e32 v181, 63, v10
	s_load_dwordx2 s[42:43], s[44:45], 0xb0
	s_waitcnt lgkmcnt(0)
	s_add_i32 s6, s37, s48
	s_lshl_b32 s14, s36, 7
	s_lshl_b32 s30, s36, 8
	v_readlane_b32 s11, v255, 21
	s_add_u32 s10, s42, s47
	s_addc_u32 s11, s43, s46
	s_add_u32 s36, s10, s30
	s_addc_u32 s37, s11, 0
	s_lshl_b32 s10, s27, 10
	s_or_b32 s10, s14, s10
	s_mul_hi_i32 s11, s10, 0x2200
	s_mulk_i32 s10, 0x2200
	v_ashrrev_i32_e32 v50, 4, v10
	s_add_u32 s10, s42, s10
	v_ashrrev_i32_e32 v51, 31, v50
	v_and_b32_e32 v177, 15, v10
	s_addc_u32 s11, s43, s11
	v_lshlrev_b64 v[52:53], 11, v[50:51]
	s_add_u32 s40, s10, 0xe010000
	v_lshl_add_u64 v[2:3], s[36:37], 0, v[52:53]
	v_lshlrev_b32_e32 v124, 4, v177
	v_mov_b32_e32 v125, v0
	s_addc_u32 s41, s11, 0
	v_lshl_add_u64 v[2:3], v[2:3], 0, v[124:125]
	s_mov_b32 s15, 0x16810000
	v_mov_b64_e32 v[4:5], s[40:41]
	s_movk_i32 s35, 0x2200
	v_add_co_u32_e32 v6, vcc, s15, v2
	v_mad_i64_i32 v[4:5], s[36:37], v50, s35, v[4:5]
	s_nop 0
	v_addc_co_u32_e32 v7, vcc, 0, v3, vcc
	s_mov_b32 s15, 0x16820000
	v_lshl_add_u64 v[4:5], v[4:5], 0, v[124:125]
	v_add_co_u32_e32 v6, vcc, s15, v2
	s_mov_b32 s15, 0x44000
	s_nop 0
	v_addc_co_u32_e32 v7, vcc, 0, v3, vcc
	v_add_co_u32_e32 v8, vcc, s15, v4
	s_mov_b32 s15, 0x16830000
	s_nop 0
	v_addc_co_u32_e32 v9, vcc, 0, v5, vcc
	v_add_co_u32_e32 v6, vcc, s15, v2
	s_mov_b32 s15, 0x88000
	s_nop 0
	v_addc_co_u32_e32 v7, vcc, 0, v3, vcc
	v_add_co_u32_e32 v8, vcc, s15, v4
	s_mov_b32 s15, 0x16840000
	s_nop 0
	v_addc_co_u32_e32 v9, vcc, 0, v5, vcc
	v_add_co_u32_e32 v2, vcc, s15, v2
	s_mov_b32 s15, 0xcc000
	s_nop 0
	v_addc_co_u32_e32 v3, vcc, 0, v3, vcc
	v_add_co_u32_e32 v4, vcc, s15, v4
	v_addc_co_u32_e32 v5, vcc, 0, v5, vcc
	v_ashrrev_i32_e32 v4, 2, v10
	v_and_b32_e32 v4, 0xffffffe0, v4
	v_add_u32_e32 v180, s6, v4
	v_ashrrev_i32_e32 v182, 6, v10
	v_and_b32_e32 v179, 1, v182
	v_mov_b32_e32 v55, v0
	v_lshlrev_b32_e32 v54, 7, v179
	v_and_b32_e32 v56, 48, v10
	v_mov_b32_e32 v57, v0
	s_mov_b32 s6, 0x14610000
	s_mov_b64 s[36:37], 0x14610000
	v_and_b32_e32 v2, 31, v223
	v_or_b32_e32 v2, v180, v2
	v_bfe_u32 v178, v10, 4, 2
	v_lshlrev_b32_e32 v51, 1, v50
	v_ashrrev_i32_e32 v3, 31, v2
	v_lshlrev_b64 v[2:3], 11, v[2:3]
	v_lshl_add_u64 v[2:3], s[42:43], 0, v[2:3]
	v_lshl_add_u64 v[2:3], v[2:3], 0, s[30:31]
	v_lshl_add_u64 v[2:3], v[2:3], 0, v[54:55]
	v_lshrrev_b32_e32 v55, 1, v50
	v_and_b32_e32 v56, 32, v232
	v_lshrrev_b32_e32 v56, 1, v56
	v_lshl_add_u64 v[6:7], v[2:3], 0, v[56:57]
	v_add_co_u32_e32 v4, vcc, s6, v6
	s_mov_b32 s6, 0x14610020
	s_nop 0
	v_addc_co_u32_e32 v5, vcc, 0, v7, vcc
	v_lshl_add_u64 v[2:3], v[6:7], 0, s[36:37]
	v_add_co_u32_e32 v6, vcc, s6, v6
	global_load_dwordx4 v[10:13], v[4:5], off
	s_nop 0
	global_load_dwordx4 v[2:5], v[2:3], off offset:64
	v_addc_co_u32_e32 v7, vcc, 0, v7, vcc
	global_load_dwordx4 v[14:17], v[6:7], off
	s_nop 0
	global_load_dwordx4 v[6:9], v[6:7], off offset:64
	v_and_b32_e32 v51, 8, v51
	v_and_b32_e32 v55, 4, v55
	v_and_b32_e32 v57, 0xffffff3, v50
	v_or3_b32 v51, v57, v51, v55
	s_movk_i32 s6, 0x110
	v_mul_lo_u32 v55, v50, s6
	v_mad_u64_u32 v[126:127], s[36:37], v51, s6, v[124:125]
	s_mov_b32 s6, 0x11000
	v_add3_u32 v127, v55, v124, s6
	v_add_u32_e32 v51, 0, v126
	v_add_u32_e32 v55, 0, v127
	s_add_i32 s6, 0, 0x11000
	v_mul_u32_u24_e32 v19, 0x110, v177
	v_add3_u32 v183, s6, v56, v19
	s_lshl_b32 s6, s26, 3
	s_and_b32 s6, s6, 0x700
	s_add_u32 s6, s42, s6
	v_add_u32_e32 v18, 0, v54
	s_addc_u32 s18, s43, 0
	v_add3_u32 v137, v18, v56, v19
	s_add_u32 s26, s6, s47
	v_mov_b64_e32 v[18:19], s[10:11]
	s_addc_u32 s27, s18, s46
	v_mad_i64_i32 v[130:131], s[10:11], v50, s35, v[18:19]
	v_mov_b32_e32 v18, 0
	s_mov_b32 s15, 0
	v_lshl_add_u64 v[128:129], s[26:27], 0, v[52:53]
	v_mov_b32_e32 v19, v18
	v_mov_b32_e32 v20, v18
	v_mov_b32_e32 v21, v18
	v_mov_b32_e32 v22, v18
	v_mov_b32_e32 v23, v18
	v_mov_b32_e32 v24, v18
	v_mov_b32_e32 v25, v18
	v_mov_b32_e32 v26, v18
	v_mov_b32_e32 v27, v18
	v_mov_b32_e32 v28, v18
	v_mov_b32_e32 v29, v18
	v_mov_b32_e32 v30, v18
	v_mov_b32_e32 v31, v18
	v_mov_b32_e32 v32, v18
	v_mov_b32_e32 v33, v18
	v_mov_b32_e32 v38, v18
	v_mov_b32_e32 v39, v18
	v_mov_b32_e32 v40, v18
	v_mov_b32_e32 v41, v18
	v_mov_b32_e32 v46, v18
	v_mov_b32_e32 v47, v18
	v_mov_b32_e32 v48, v18
	v_mov_b32_e32 v49, v18
	v_mov_b32_e32 v62, v18
	v_mov_b32_e32 v63, v18
	v_mov_b32_e32 v64, v18
	v_mov_b32_e32 v65, v18
	v_mov_b32_e32 v74, v18
	v_mov_b32_e32 v75, v18
	v_mov_b32_e32 v76, v18
	v_mov_b32_e32 v77, v18
	v_mov_b32_e32 v34, v18
	v_mov_b32_e32 v35, v18
	v_mov_b32_e32 v36, v18
	v_mov_b32_e32 v37, v18
	v_mov_b32_e32 v42, v18
	v_mov_b32_e32 v43, v18
	v_mov_b32_e32 v44, v18
	v_mov_b32_e32 v45, v18
	v_mov_b32_e32 v50, v18
	v_mov_b32_e32 v51, v18
	v_mov_b32_e32 v52, v18
	v_mov_b32_e32 v53, v18
	v_mov_b32_e32 v54, v18
	v_mov_b32_e32 v55, v18
	v_mov_b32_e32 v56, v18
	v_mov_b32_e32 v57, v18
	v_mov_b32_e32 v58, v18
	v_mov_b32_e32 v59, v18
	v_mov_b32_e32 v60, v18
	v_mov_b32_e32 v61, v18
	v_mov_b32_e32 v66, v18
	v_mov_b32_e32 v67, v18
	v_mov_b32_e32 v68, v18
	v_mov_b32_e32 v69, v18
	v_mov_b32_e32 v70, v18
	v_mov_b32_e32 v71, v18
	v_mov_b32_e32 v72, v18
	v_mov_b32_e32 v73, v18
	v_mov_b32_e32 v78, v18
	v_mov_b32_e32 v79, v18
	v_mov_b32_e32 v80, v18
	v_mov_b32_e32 v81, v18
	v_mov_b32_e32 v122, v18
	v_mov_b32_e32 v123, v18
	s_mov_b32 s11, 0xe054000
	s_mov_b32 s18, 0x16870000
	s_mov_b32 s26, 0xe098000
	s_mov_b32 s27, 0x16880000
	s_mov_b32 s30, 0xe0dc000
	s_mov_b64 s[36:37], 0x40000
	s_waitcnt lgkmcnt(0)
	s_barrier
	s_waitcnt vmcnt(0) lgkmcnt(0)
	v_writelane_b32 v175, s64, 0
	v_writelane_b32 v175, s65, 1
	v_writelane_b32 v175, s66, 2
	v_writelane_b32 v175, s67, 3
	v_writelane_b32 v175, s68, 4
	v_writelane_b32 v175, s69, 5
	v_writelane_b32 v175, s70, 6
	v_writelane_b32 v175, s71, 7
	v_writelane_b32 v175, s72, 8
	v_writelane_b32 v175, s73, 9
	v_writelane_b32 v175, s74, 10
	v_writelane_b32 v175, s75, 11
	v_writelane_b32 v175, s76, 12
	v_writelane_b32 v175, s77, 13
	v_writelane_b32 v175, s78, 14
	v_writelane_b32 v175, s79, 15
	v_lshrrev_b32_e32 v200, 4, v232
	v_lshlrev_b32_e32 v201, 11, v200
	v_mul_u32_u24_e32 v202, 0x2200, v200
	v_sub_co_u32_e32 v138, vcc, v128, v201
	s_nop 1
	v_subbrev_co_u32_e32 v139, vcc, 0, v129, vcc
	v_sub_co_u32_e32 v140, vcc, v130, v202
	s_nop 1
	v_subbrev_co_u32_e32 v141, vcc, 0, v131, vcc
	s_nop 1
	v_readfirstlane_b32 s64, v138
	v_readfirstlane_b32 s65, v139
	v_readfirstlane_b32 s72, v140
	v_readfirstlane_b32 s73, v141
	v_and_b32_e32 v203, 15, v200
	v_xor_b32_e32 v203, v203, v177
	v_and_b32_e32 v204, 0x13, v200
	v_lshlrev_b32_e32 v205, 1, v200
	v_and_b32_e32 v205, 8, v205
	v_lshrrev_b32_e32 v206, 1, v200
	v_and_b32_e32 v206, 4, v206
	v_or3_b32 v204, v204, v205, v206
	v_lshlrev_b32_e32 v204, 11, v204
	v_lshl_add_u32 v124, v203, 4, v204
	v_lshl_add_u32 v125, v203, 4, v202
	s_add_u32 s66, s64, s97
	s_addc_u32 s67, s65, 0
	s_sub_u32 s66, s66, 0x40000
	s_subb_u32 s67, s67, 0
	s_add_u32 s68, s64, s18
	s_addc_u32 s69, s65, 0
	s_sub_u32 s68, s68, 0x40000
	s_subb_u32 s69, s69, 0
	s_add_u32 s70, s64, s27
	s_addc_u32 s71, s65, 0
	s_sub_u32 s70, s70, 0x40000
	s_subb_u32 s71, s71, 0
	s_add_u32 s64, s64, s96
	s_addc_u32 s65, s65, 0
	s_sub_u32 s64, s64, 0x40000
	s_subb_u32 s65, s65, 0
	s_add_u32 s74, s72, s11
	s_addc_u32 s75, s73, 0
	s_add_u32 s76, s72, s26
	s_addc_u32 s77, s73, 0
	s_add_u32 s78, s72, s30
	s_addc_u32 s79, s73, 0
	s_add_u32 s72, s72, s91
	s_addc_u32 s73, s73, 0
	v_lshrrev_b32_e32 v205, 6, v232
	s_nop 0
	v_readfirstlane_b32 s11, v205
	s_nop 3
	s_lshl_b32 s11, s11, 10
	s_add_i32 m0, s11, 0x0
	s_nop 0
	global_load_lds_dwordx4 v124, s[64:65]
	s_add_i32 m0, s11, 0x2000
	s_nop 0
	global_load_lds_dwordx4 v124, s[66:67]
	s_add_i32 m0, s11, 0x4000
	s_nop 0
	global_load_lds_dwordx4 v124, s[68:69]
	s_add_i32 m0, s11, 0x6000
	s_nop 0
	global_load_lds_dwordx4 v124, s[70:71]
	s_add_i32 s6, s11, 0x10000
	s_add_i32 m0, s6, 0x0
	s_nop 0
	global_load_lds_dwordx4 v125, s[72:73]
	s_add_i32 m0, s6, 0x2000
	s_nop 0
	global_load_lds_dwordx4 v125, s[74:75]
	s_add_i32 m0, s6, 0x4000
	s_nop 0
	global_load_lds_dwordx4 v125, s[76:77]
	s_add_i32 m0, s6, 0x6000
	s_nop 0
	global_load_lds_dwordx4 v125, s[78:79]
	s_add_u32 s64, s64, 0x40000
	s_addc_u32 s65, s65, 0
	s_add_u32 s72, s72, 0x100
	s_addc_u32 s73, s73, 0
	s_add_u32 s66, s66, 0x40000
	s_addc_u32 s67, s67, 0
	s_add_u32 s74, s74, 0x100
	s_addc_u32 s75, s75, 0
	s_add_u32 s68, s68, 0x40000
	s_addc_u32 s69, s69, 0
	s_add_u32 s76, s76, 0x100
	s_addc_u32 s77, s77, 0
	s_add_u32 s70, s70, 0x40000
	s_addc_u32 s71, s71, 0
	s_add_u32 s78, s78, 0x100
	s_addc_u32 s79, s79, 0
	v_and_b32_e32 v200, 31, v223
	v_lshrrev_b32_e32 v201, 5, v223
	v_and_b32_e32 v202, 15, v200
	v_lshlrev_b32_e32 v200, 8, v200
	v_lshlrev_b32_e32 v203, 3, v179
	v_or3_b32 v204, v203, v201, 0
	v_xor_b32_e32 v204, v204, v202
	v_lshl_add_u32 v82, v204, 4, v200
	v_or3_b32 v204, v203, v201, 2
	v_xor_b32_e32 v204, v204, v202
	v_lshl_add_u32 v83, v204, 4, v200
	v_or3_b32 v204, v203, v201, 4
	v_xor_b32_e32 v204, v204, v202
	v_lshl_add_u32 v84, v204, 4, v200
	v_or3_b32 v204, v203, v201, 6
	v_xor_b32_e32 v204, v204, v202
	v_lshl_add_u32 v85, v204, 4, v200
	v_add_u32_e32 v200, 0x10000, v200
	v_or_b32_e32 v204, 0, v201
	v_xor_b32_e32 v204, v204, v202
	v_lshl_add_u32 v86, v204, 4, v200
	v_or_b32_e32 v204, 2, v201
	v_xor_b32_e32 v204, v204, v202
	v_lshl_add_u32 v87, v204, 4, v200
	v_or_b32_e32 v204, 4, v201
	v_xor_b32_e32 v204, v204, v202
	v_lshl_add_u32 v88, v204, 4, v200
	v_or_b32_e32 v204, 6, v201
	v_xor_b32_e32 v204, v204, v202
	v_lshl_add_u32 v89, v204, 4, v200
	v_or_b32_e32 v204, 8, v201
	v_xor_b32_e32 v204, v204, v202
	v_lshl_add_u32 v90, v204, 4, v200
	v_or_b32_e32 v204, 10, v201
	v_xor_b32_e32 v204, v204, v202
	v_lshl_add_u32 v91, v204, 4, v200
	v_or_b32_e32 v204, 12, v201
	v_xor_b32_e32 v204, v204, v202
	v_lshl_add_u32 v92, v204, 4, v200
	v_or_b32_e32 v204, 14, v201
	v_xor_b32_e32 v204, v204, v202
	v_lshl_add_u32 v93, v204, 4, v200
	s_mov_b32 s15, 0
	s_waitcnt vmcnt(0)
	s_barrier
	.p2align 6
.Lattn_nf_loop:
	ds_read_b128 v[98:101], v82 offset:0
	ds_read_b128 v[102:105], v83 offset:0
	ds_read_b128 v[106:109], v84 offset:0
	ds_read_b128 v[110:113], v85 offset:0
	s_and_b32 s10, s15, 1
	s_xor_b32 s10, s10, 1
	s_lshl_b32 s10, s10, 15
	s_add_i32 s10, s10, s11
	s_add_i32 m0, s10, 0x0
	s_nop 0
	global_load_lds_dwordx4 v124, s[64:65]
	s_add_i32 m0, s10, 0x2000
	s_nop 0
	global_load_lds_dwordx4 v124, s[66:67]
	s_add_i32 m0, s10, 0x4000
	s_nop 0
	global_load_lds_dwordx4 v124, s[68:69]
	s_add_i32 m0, s10, 0x6000
	s_nop 0
	global_load_lds_dwordx4 v124, s[70:71]
	v_add_u32_e32 v124, s36, v124
	s_add_i32 s6, s10, 0x10000
	s_add_i32 m0, s6, 0x0
	s_nop 0
	global_load_lds_dwordx4 v125, s[72:73]
	s_add_i32 m0, s6, 0x2000
	s_nop 0
	global_load_lds_dwordx4 v125, s[74:75]
	s_add_i32 m0, s6, 0x4000
	s_nop 0
	global_load_lds_dwordx4 v125, s[76:77]
	s_add_i32 m0, s6, 0x6000
	s_nop 0
	global_load_lds_dwordx4 v125, s[78:79]
	v_add_u32_e32 v125, s38, v125
	s_waitcnt lgkmcnt(3)
	v_mfma_f32_32x32x16_bf16 v[138:153], v[98:101], v[10:13], 0
	ds_read_b128 v[98:101], v82 offset:8192
	s_waitcnt lgkmcnt(3)
	v_mfma_f32_32x32x16_bf16 v[138:153], v[102:105], v[14:17], v[138:153]
	ds_read_b128 v[102:105], v83 offset:8192
	s_waitcnt lgkmcnt(3)
	v_mfma_f32_32x32x16_bf16 v[138:153], v[106:109], v[2:5], v[138:153]
	ds_read_b128 v[106:109], v84 offset:8192
	s_waitcnt lgkmcnt(3)
	v_mfma_f32_32x32x16_bf16 v[138:153], v[110:113], v[6:9], v[138:153]
	ds_read_b128 v[110:113], v85 offset:8192
	ds_read_b128 v[128:131], v86 offset:0
	ds_read_b128 v[184:187], v86 offset:8192
	ds_read_b128 v[188:191], v86 offset:16384
	ds_read_b128 v[192:195], v86 offset:24576
	s_waitcnt lgkmcnt(7)
	v_mfma_f32_32x32x16_bf16 v[154:169], v[98:101], v[10:13], 0
	ds_read_b128 v[98:101], v82 offset:16384
	s_nop 3
	v_exp_f32_e32 v138, v138
	v_exp_f32_e32 v139, v139
	v_exp_f32_e32 v140, v140
	v_exp_f32_e32 v141, v141
	v_exp_f32_e32 v142, v142
	v_exp_f32_e32 v143, v143
	s_waitcnt lgkmcnt(7)
	v_mfma_f32_32x32x16_bf16 v[154:169], v[102:105], v[14:17], v[154:169]
	ds_read_b128 v[102:105], v83 offset:16384
	v_exp_f32_e32 v144, v144
	v_exp_f32_e32 v145, v145
	v_add_f32_e32 v122, v138, v122
	v_add_f32_e32 v122, v139, v122
	v_add_f32_e32 v122, v140, v122
	v_add_f32_e32 v122, v141, v122
	v_add_f32_e32 v122, v142, v122
	v_add_f32_e32 v122, v143, v122
	v_add_f32_e32 v122, v144, v122
	v_add_f32_e32 v122, v145, v122
	v_cvt_pk_bf16_f32 v114, v138, v139
	v_cvt_pk_bf16_f32 v115, v140, v141
	v_cvt_pk_bf16_f32 v116, v142, v143
	v_cvt_pk_bf16_f32 v117, v144, v145
	ds_read_b128 v[196:199], v87 offset:0
	ds_read_b128 v[216:219], v87 offset:8192
	ds_read_b128 v[200:203], v87 offset:16384
	ds_read_b128 v[204:207], v87 offset:24576
	s_waitcnt lgkmcnt(11)
	v_mfma_f32_32x32x16_bf16 v[154:169], v[106:109], v[2:5], v[154:169]
	ds_read_b128 v[106:109], v84 offset:16384
	v_exp_f32_e32 v146, v146
	v_exp_f32_e32 v147, v147
	s_waitcnt lgkmcnt(11)
	v_mfma_f32_32x32x16_bf16 v[154:169], v[110:113], v[6:9], v[154:169]
	ds_read_b128 v[110:113], v85 offset:16384
	v_exp_f32_e32 v148, v148
	v_exp_f32_e32 v149, v149
	s_waitcnt lgkmcnt(11)
	v_mfma_f32_32x32x16_bf16 v[18:33], v[128:131], v[114:117], v[18:33]
	v_exp_f32_e32 v150, v150
	v_exp_f32_e32 v151, v151
	s_waitcnt lgkmcnt(10)
	v_mfma_f32_32x32x16_bf16 v[34:49], v[184:187], v[114:117], v[34:49]
	v_exp_f32_e32 v152, v152
	v_exp_f32_e32 v153, v153
	s_waitcnt lgkmcnt(9)
	v_mfma_f32_32x32x16_bf16 v[50:65], v[188:191], v[114:117], v[50:65]
	v_add_f32_e32 v122, v146, v122
	v_add_f32_e32 v122, v147, v122
	v_add_f32_e32 v122, v148, v122
	v_add_f32_e32 v122, v149, v122
	s_waitcnt lgkmcnt(8)
	v_mfma_f32_32x32x16_bf16 v[66:81], v[192:195], v[114:117], v[66:81]
	v_add_f32_e32 v122, v150, v122
	v_add_f32_e32 v122, v151, v122
	v_add_f32_e32 v122, v152, v122
	v_add_f32_e32 v122, v153, v122
	v_cvt_pk_bf16_f32 v118, v146, v147
	v_cvt_pk_bf16_f32 v119, v148, v149
	v_cvt_pk_bf16_f32 v120, v150, v151
	v_cvt_pk_bf16_f32 v121, v152, v153
	ds_read_b128 v[128:131], v88 offset:0
	ds_read_b128 v[184:187], v88 offset:8192
	ds_read_b128 v[188:191], v88 offset:16384
	ds_read_b128 v[192:195], v88 offset:24576
	s_waitcnt lgkmcnt(11)
	v_mfma_f32_32x32x16_bf16 v[138:153], v[98:101], v[10:13], 0
	ds_read_b128 v[98:101], v82 offset:24576
	v_exp_f32_e32 v154, v154
	v_exp_f32_e32 v155, v155
	s_waitcnt lgkmcnt(11)
	v_mfma_f32_32x32x16_bf16 v[138:153], v[102:105], v[14:17], v[138:153]
	ds_read_b128 v[102:105], v83 offset:24576
	v_exp_f32_e32 v156, v156
	v_exp_f32_e32 v157, v157
	s_waitcnt lgkmcnt(11)
	v_mfma_f32_32x32x16_bf16 v[18:33], v[196:199], v[118:121], v[18:33]
	v_exp_f32_e32 v158, v158
	v_exp_f32_e32 v159, v159
	s_waitcnt lgkmcnt(10)
	v_mfma_f32_32x32x16_bf16 v[34:49], v[216:219], v[118:121], v[34:49]
	v_exp_f32_e32 v160, v160
	v_exp_f32_e32 v161, v161
	s_waitcnt lgkmcnt(9)
	v_mfma_f32_32x32x16_bf16 v[50:65], v[200:203], v[118:121], v[50:65]
	v_add_f32_e32 v122, v154, v122
	v_add_f32_e32 v122, v155, v122
	v_add_f32_e32 v122, v156, v122
	v_add_f32_e32 v122, v157, v122
	s_waitcnt lgkmcnt(8)
	v_mfma_f32_32x32x16_bf16 v[66:81], v[204:207], v[118:121], v[66:81]
	v_add_f32_e32 v122, v158, v122
	v_add_f32_e32 v122, v159, v122
	v_add_f32_e32 v122, v160, v122
	v_add_f32_e32 v122, v161, v122
	v_cvt_pk_bf16_f32 v114, v154, v155
	v_cvt_pk_bf16_f32 v115, v156, v157
	v_cvt_pk_bf16_f32 v116, v158, v159
	v_cvt_pk_bf16_f32 v117, v160, v161
	ds_read_b128 v[196:199], v89 offset:0
	ds_read_b128 v[216:219], v89 offset:8192
	ds_read_b128 v[200:203], v89 offset:16384
	ds_read_b128 v[204:207], v89 offset:24576
	s_waitcnt lgkmcnt(11)
	v_mfma_f32_32x32x16_bf16 v[138:153], v[106:109], v[2:5], v[138:153]
	ds_read_b128 v[106:109], v84 offset:24576
	v_exp_f32_e32 v162, v162
	v_exp_f32_e32 v163, v163
	s_waitcnt lgkmcnt(11)
	v_mfma_f32_32x32x16_bf16 v[138:153], v[110:113], v[6:9], v[138:153]
	ds_read_b128 v[110:113], v85 offset:24576
	v_exp_f32_e32 v164, v164
	v_exp_f32_e32 v165, v165
	s_waitcnt lgkmcnt(11)
	v_mfma_f32_32x32x16_bf16 v[18:33], v[128:131], v[114:117], v[18:33]
	v_exp_f32_e32 v166, v166
	v_exp_f32_e32 v167, v167
	s_waitcnt lgkmcnt(10)
	v_mfma_f32_32x32x16_bf16 v[34:49], v[184:187], v[114:117], v[34:49]
	v_exp_f32_e32 v168, v168
	v_exp_f32_e32 v169, v169
	s_waitcnt lgkmcnt(9)
	v_mfma_f32_32x32x16_bf16 v[50:65], v[188:191], v[114:117], v[50:65]
	v_add_f32_e32 v122, v162, v122
	v_add_f32_e32 v122, v163, v122
	v_add_f32_e32 v122, v164, v122
	v_add_f32_e32 v122, v165, v122
	s_waitcnt lgkmcnt(8)
	v_mfma_f32_32x32x16_bf16 v[66:81], v[192:195], v[114:117], v[66:81]
	v_add_f32_e32 v122, v166, v122
	v_add_f32_e32 v122, v167, v122
	v_add_f32_e32 v122, v168, v122
	v_add_f32_e32 v122, v169, v122
	v_cvt_pk_bf16_f32 v118, v162, v163
	v_cvt_pk_bf16_f32 v119, v164, v165
	v_cvt_pk_bf16_f32 v120, v166, v167
	v_cvt_pk_bf16_f32 v121, v168, v169
	ds_read_b128 v[128:131], v90 offset:0
	ds_read_b128 v[184:187], v90 offset:8192
	ds_read_b128 v[188:191], v90 offset:16384
	ds_read_b128 v[192:195], v90 offset:24576
	s_waitcnt lgkmcnt(11)
	v_mfma_f32_32x32x16_bf16 v[154:169], v[98:101], v[10:13], 0
	v_exp_f32_e32 v138, v138
	v_exp_f32_e32 v139, v139
	s_waitcnt lgkmcnt(10)
	v_mfma_f32_32x32x16_bf16 v[154:169], v[102:105], v[14:17], v[154:169]
	v_exp_f32_e32 v140, v140
	v_exp_f32_e32 v141, v141
	s_waitcnt lgkmcnt(9)
	v_mfma_f32_32x32x16_bf16 v[18:33], v[196:199], v[118:121], v[18:33]
	v_exp_f32_e32 v142, v142
	v_exp_f32_e32 v143, v143
	s_waitcnt lgkmcnt(8)
	v_mfma_f32_32x32x16_bf16 v[34:49], v[216:219], v[118:121], v[34:49]
	v_exp_f32_e32 v144, v144
	v_exp_f32_e32 v145, v145
	s_waitcnt lgkmcnt(7)
	v_mfma_f32_32x32x16_bf16 v[50:65], v[200:203], v[118:121], v[50:65]
	v_add_f32_e32 v122, v138, v122
	v_add_f32_e32 v122, v139, v122
	v_add_f32_e32 v122, v140, v122
	v_add_f32_e32 v122, v141, v122
	s_waitcnt lgkmcnt(6)
	v_mfma_f32_32x32x16_bf16 v[66:81], v[204:207], v[118:121], v[66:81]
	v_add_f32_e32 v122, v142, v122
	v_add_f32_e32 v122, v143, v122
	v_add_f32_e32 v122, v144, v122
	v_add_f32_e32 v122, v145, v122
	v_cvt_pk_bf16_f32 v114, v138, v139
	v_cvt_pk_bf16_f32 v115, v140, v141
	v_cvt_pk_bf16_f32 v116, v142, v143
	v_cvt_pk_bf16_f32 v117, v144, v145
	ds_read_b128 v[196:199], v91 offset:0
	ds_read_b128 v[216:219], v91 offset:8192
	ds_read_b128 v[200:203], v91 offset:16384
	ds_read_b128 v[204:207], v91 offset:24576
	s_waitcnt lgkmcnt(9)
	v_mfma_f32_32x32x16_bf16 v[154:169], v[106:109], v[2:5], v[154:169]
	v_exp_f32_e32 v146, v146
	v_exp_f32_e32 v147, v147
	s_waitcnt lgkmcnt(8)
	v_mfma_f32_32x32x16_bf16 v[154:169], v[110:113], v[6:9], v[154:169]
	v_exp_f32_e32 v148, v148
	v_exp_f32_e32 v149, v149
	s_waitcnt lgkmcnt(7)
	v_mfma_f32_32x32x16_bf16 v[18:33], v[128:131], v[114:117], v[18:33]
	v_exp_f32_e32 v150, v150
	v_exp_f32_e32 v151, v151
	s_waitcnt lgkmcnt(6)
	v_mfma_f32_32x32x16_bf16 v[34:49], v[184:187], v[114:117], v[34:49]
	v_exp_f32_e32 v152, v152
	v_exp_f32_e32 v153, v153
	s_waitcnt lgkmcnt(5)
	v_mfma_f32_32x32x16_bf16 v[50:65], v[188:191], v[114:117], v[50:65]
	v_add_f32_e32 v122, v146, v122
	v_add_f32_e32 v122, v147, v122
	v_add_f32_e32 v122, v148, v122
	v_add_f32_e32 v122, v149, v122
	s_waitcnt lgkmcnt(4)
	v_mfma_f32_32x32x16_bf16 v[66:81], v[192:195], v[114:117], v[66:81]
	v_add_f32_e32 v122, v150, v122
	v_add_f32_e32 v122, v151, v122
	v_add_f32_e32 v122, v152, v122
	v_add_f32_e32 v122, v153, v122
	v_cvt_pk_bf16_f32 v118, v146, v147
	v_cvt_pk_bf16_f32 v119, v148, v149
	v_cvt_pk_bf16_f32 v120, v150, v151
	v_cvt_pk_bf16_f32 v121, v152, v153
	ds_read_b128 v[128:131], v92 offset:0
	ds_read_b128 v[184:187], v92 offset:8192
	ds_read_b128 v[188:191], v92 offset:16384
	ds_read_b128 v[192:195], v92 offset:24576
	s_waitcnt lgkmcnt(7)
	v_mfma_f32_32x32x16_bf16 v[18:33], v[196:199], v[118:121], v[18:33]
	v_exp_f32_e32 v154, v154
	v_exp_f32_e32 v155, v155
	v_exp_f32_e32 v156, v156
	s_waitcnt lgkmcnt(6)
	v_mfma_f32_32x32x16_bf16 v[34:49], v[216:219], v[118:121], v[34:49]
	v_exp_f32_e32 v157, v157
	v_exp_f32_e32 v158, v158
	v_exp_f32_e32 v159, v159
	s_waitcnt lgkmcnt(5)
	v_mfma_f32_32x32x16_bf16 v[50:65], v[200:203], v[118:121], v[50:65]
	v_exp_f32_e32 v160, v160
	v_exp_f32_e32 v161, v161
	v_add_f32_e32 v122, v154, v122
	v_add_f32_e32 v122, v155, v122
	s_waitcnt lgkmcnt(4)
	v_mfma_f32_32x32x16_bf16 v[66:81], v[204:207], v[118:121], v[66:81]
	v_add_f32_e32 v122, v156, v122
	v_add_f32_e32 v122, v157, v122
	v_add_f32_e32 v122, v158, v122
	v_add_f32_e32 v122, v159, v122
	v_add_f32_e32 v122, v160, v122
	v_add_f32_e32 v122, v161, v122
	v_cvt_pk_bf16_f32 v114, v154, v155
	v_cvt_pk_bf16_f32 v115, v156, v157
	v_cvt_pk_bf16_f32 v116, v158, v159
	v_cvt_pk_bf16_f32 v117, v160, v161
	ds_read_b128 v[196:199], v93 offset:0
	ds_read_b128 v[216:219], v93 offset:8192
	ds_read_b128 v[200:203], v93 offset:16384
	ds_read_b128 v[204:207], v93 offset:24576
	s_waitcnt lgkmcnt(7)
	v_mfma_f32_32x32x16_bf16 v[18:33], v[128:131], v[114:117], v[18:33]
	v_exp_f32_e32 v162, v162
	v_exp_f32_e32 v163, v163
	v_exp_f32_e32 v164, v164
	s_waitcnt lgkmcnt(6)
	v_mfma_f32_32x32x16_bf16 v[34:49], v[184:187], v[114:117], v[34:49]
	v_exp_f32_e32 v165, v165
	v_exp_f32_e32 v166, v166
	v_exp_f32_e32 v167, v167
	s_waitcnt lgkmcnt(5)
	v_mfma_f32_32x32x16_bf16 v[50:65], v[188:191], v[114:117], v[50:65]
	v_exp_f32_e32 v168, v168
	v_exp_f32_e32 v169, v169
	v_add_f32_e32 v122, v162, v122
	v_add_f32_e32 v122, v163, v122
	s_waitcnt lgkmcnt(4)
	v_mfma_f32_32x32x16_bf16 v[66:81], v[192:195], v[114:117], v[66:81]
	v_add_f32_e32 v122, v164, v122
	v_add_f32_e32 v122, v165, v122
	v_add_f32_e32 v122, v166, v122
	v_add_f32_e32 v122, v167, v122
	v_add_f32_e32 v122, v168, v122
	v_add_f32_e32 v122, v169, v122
	v_cvt_pk_bf16_f32 v118, v162, v163
	v_cvt_pk_bf16_f32 v119, v164, v165
	v_cvt_pk_bf16_f32 v120, v166, v167
	v_cvt_pk_bf16_f32 v121, v168, v169
	s_waitcnt lgkmcnt(3)
	s_nop 0
	v_mfma_f32_32x32x16_bf16 v[18:33], v[196:199], v[118:121], v[18:33]
	s_waitcnt lgkmcnt(2)
	v_mfma_f32_32x32x16_bf16 v[34:49], v[216:219], v[118:121], v[34:49]
	s_waitcnt lgkmcnt(1)
	v_mfma_f32_32x32x16_bf16 v[50:65], v[200:203], v[118:121], v[50:65]
	s_waitcnt lgkmcnt(0)
	v_mfma_f32_32x32x16_bf16 v[66:81], v[204:207], v[118:121], v[66:81]
	v_xor_b32_e32 v82, 0x8000, v82
	v_xor_b32_e32 v83, 0x8000, v83
	v_xor_b32_e32 v84, 0x8000, v84
	v_xor_b32_e32 v85, 0x8000, v85
	v_xor_b32_e32 v86, 0x8000, v86
	v_xor_b32_e32 v87, 0x8000, v87
	v_xor_b32_e32 v88, 0x8000, v88
	v_xor_b32_e32 v89, 0x8000, v89
	v_xor_b32_e32 v90, 0x8000, v90
	v_xor_b32_e32 v91, 0x8000, v91
	v_xor_b32_e32 v92, 0x8000, v92
	v_xor_b32_e32 v93, 0x8000, v93
	s_waitcnt vmcnt(0)
	s_waitcnt lgkmcnt(0)
	s_barrier
	s_add_i32 s15, s15, 1
	s_cmp_eq_u32 s15, 34
	s_cbranch_scc0 .Lattn_nf_loop
	v_readlane_b32 s64, v175, 0
	v_readlane_b32 s65, v175, 1
	v_readlane_b32 s66, v175, 2
	v_readlane_b32 s67, v175, 3
	v_readlane_b32 s68, v175, 4
	v_readlane_b32 s69, v175, 5
	v_readlane_b32 s70, v175, 6
	v_readlane_b32 s71, v175, 7
	v_readlane_b32 s72, v175, 8
	v_readlane_b32 s73, v175, 9
	v_readlane_b32 s74, v175, 10
	v_readlane_b32 s75, v175, 11
	v_readlane_b32 s76, v175, 12
	v_readlane_b32 s77, v175, 13
	v_readlane_b32 s78, v175, 14
	v_readlane_b32 s79, v175, 15
	s_nop 4
	s_mov_b32 s10, 0x3fb8aa3b
	s_mov_b32 s11, 0xc2ce8ed0
	s_mov_b32 s6, 0x42b17218
	v_cmp_eq_u32_e64 s[40:41], 0, v179
	s_lshl_b32 s30, s14, 1
	v_lshlrev_b32_e32 v196, 3, v178
	v_mov_b32_e32 v197, 0
	v_lshlrev_b32_e32 v198, 4, v179
	v_or3_b32 v198, v198, v177, v180
	v_ashrrev_i32_e32 v199, 31, v198
	v_lshlrev_b64 v[198:199], 11, v[198:199]
	s_mov_b64 s[100:101], 0x18a10000
	v_lshl_add_u64 v[198:199], s[42:43], 0, v[198:199]
	v_lshl_add_u64 v[198:199], v[198:199], 0, s[30:31]
	v_lshl_add_u64 v[198:199], v[198:199], 0, v[196:197]
	v_lshl_add_u64 v[198:199], v[198:199], 0, s[100:101]
	global_load_dwordx2 v[146:147], v[198:199], off
	global_load_dwordx2 v[148:149], v[198:199], off offset:32
	global_load_dwordx2 v[150:151], v[198:199], off offset:64
	global_load_dwordx2 v[152:153], v[198:199], off offset:96
	global_load_dwordx2 v[188:189], v[198:199], off offset:128
	global_load_dwordx2 v[190:191], v[198:199], off offset:160
	global_load_dwordx2 v[192:193], v[198:199], off offset:192
	global_load_dwordx2 v[194:195], v[198:199], off offset:224
	s_mov_b64 s[100:101], exec
	s_and_b64 exec, exec, s[4:5]
	s_cbranch_execz .Lpop_skip
	v_readlane_b32 s14, v255, 22
	v_readlane_b32 s15, v255, 23
	v_mov_b32_e32 v224, 1
	s_nop 4
	global_atomic_add v224, v0, v224, s[14:15] sc0
